# static priority raise (bid>=256) also over expert_dots and expert_vsum phases
# baseline (speedup 1.0000x reference)
; DI int otid() { int t = threadIdx.x; asm volatile("" : "+v"(t)); return t; }
; DI int obid() { int t = blockIdx.x; asm volatile("" : "+s"(t)); return t; }
; DI void expert_dots(const Params& p, int nrows, char* smem) {
;   const int tid = otid(), wave = tid >> 6, lane = tid & 63, g = lane >> 4, s = lane & 15;
;   const int bid = obid(), x = bid & 7, jx = bid >> 3, wpx = (gridDim.x + 7 - x) >> 3;
;   u32* list = (u32*)smem + wave * 128;
;   const int* IDX = (const int*)(p.S + OFF_IDX);
;   const float* GATE = (const float*)(p.S + OFF_GATE);
;   u16* AV16 = (u16*)(p.S + OFF_PU);
;   const unsigned char* PU = (const unsigned char*)(p.PT + PT_U) + s * 16;
;   const float* PSU = (const float*)(p.PT + PT_SC);
;   const float* PSV = PSU + 16384;
;   const int tstep = wpx * 4;
;   int t = jx * 4 + wave;
;   int ni0 = 0, ni1 = 0;
;   uint4 nh[8];
;   auto prefetch = [&](int tt) {
;     { const u32 w2 = ((const u32*)IDX)[(size_t)tt * 64 + lane]; ni0 = (int)(w2 & 0xffffu); ni1 = (int)(w2 >> 16); }
; #pragma unroll
;     for (int c = 0; c < 4; c++) {
;       const u16* hp = p.H + (size_t)tt * D + (c * 16 + s) * 16;
;       nh[2 * c] = *(const uint4*)(hp); nh[2 * c + 1] = *(const uint4*)(hp + 8);
;     }
;   };
;   auto dot_row = [&](const int4 (&uu)[4], const f2 (&hf)[32]) {
;     const int uw[16] = {uu[0].x, uu[0].y, uu[0].z, uu[0].w, uu[1].x, uu[1].y, uu[1].z, uu[1].w,
;                         uu[2].x, uu[2].y, uu[2].z, uu[2].w, uu[3].x, uu[3].y, uu[3].z, uu[3].w};
;     f2 acc = {0.f, 0.f}, acc2 = {0.f, 0.f};
; #pragma unroll
;     for (int j = 0; j < 16; j++) {
;       acc = __builtin_elementwise_fma(__builtin_amdgcn_cvt_pk_f32_fp8(uw[j], false), hf[2 * j], acc);
;       acc2 = __builtin_elementwise_fma(__builtin_amdgcn_cvt_pk_f32_fp8(uw[j], true), hf[2 * j + 1], acc2);
;     }
;     return row16_sum((acc.x + acc.y) + (acc2.x + acc2.y));
;   };
;   if (t < nrows) prefetch(t);
.LBB0_1071:
	s_andn2_b64 vcc, exec, s[0:1]
	s_cbranch_vccnz .LBB0_1142
	s_cmp_ge_u32 s74, 0x100
	s_cbranch_scc0 .Lprio_ph_d
	s_setprio 1
.Lprio_ph_d:
	s_waitcnt vmcnt(3) lgkmcnt(0)
	v_mov_b32_e32 v1, v220
	s_mov_b32 s0, s74
	s_ashr_i32 s1, s0, 1
	v_ashrrev_i32_e32 v0, 6, v1
	s_and_b32 s1, s1, -4
	v_add_u32_e32 v104, s1, v0
	v_cmp_gt_i32_e32 vcc, s54, v104
	s_and_saveexec_b64 s[40:41], vcc
	s_cbranch_execz .LBB0_1088
	s_and_b32 s24, s0, 7
	v_readlane_b32 s0, v252, 36
	s_sub_i32 s0, s0, s24
	s_lshr_b32 s0, s0, 1
	v_and_b32_e32 v107, 15, v1
	s_and_b32 s36, s0, 0x7ffffffc
	v_ashrrev_i32_e32 v105, 31, v104
	v_readlane_b32 s0, v251, 37
	s_waitcnt vmcnt(2)
	v_and_b32_e32 v4, 63, v1
	v_bfe_u32 v106, v1, 4, 2
	v_lshlrev_b32_e32 v108, 9, v0
	v_lshlrev_b32_e32 v196, 4, v107
	v_lshlrev_b64 v[0:1], 8, v[104:105]
	v_readlane_b32 s1, v251, 38
	v_lshl_add_u64 v[64:65], s[18:19], 0, v[196:197]
	v_lshlrev_b32_e32 v196, 2, v4
	v_lshl_add_u64 v[0:1], s[0:1], 0, v[0:1]
	v_lshl_add_u64 v[0:1], v[0:1], 0, v[196:197]
	global_load_dword v0, v[0:1], off
	v_lshlrev_b32_e32 v2, 5, v107
	v_mov_b32_e32 v3, v197
	v_lshlrev_b32_e32 v109, 17, v4
	v_lshl_add_u64 v[66:67], s[0:1], 0, v[196:197]
	v_lshl_or_b32 v110, v107, 2, v106
	v_lshl_add_u64 v[68:69], s[10:11], 0, v[2:3]
	v_or_b32_e32 v111, 0x10000, v109
	s_mov_b64 s[42:43], 0
	s_waitcnt vmcnt(0)
	v_and_b32_e32 v73, 0xffff, v0
	v_lshrrev_b32_e32 v72, 16, v0
	v_lshlrev_b64 v[0:1], 11, v[104:105]
	v_lshl_add_u64 v[0:1], s[10:11], 0, v[0:1]
	v_lshl_add_u64 v[0:1], v[0:1], 0, v[2:3]
	global_load_dwordx4 v[32:35], v[0:1], off offset:16
	global_load_dwordx4 v[48:51], v[0:1], off
	global_load_dwordx4 v[36:39], v[0:1], off offset:528
	global_load_dwordx4 v[52:55], v[0:1], off offset:512
	global_load_dwordx4 v[40:43], v[0:1], off offset:1040
	global_load_dwordx4 v[56:59], v[0:1], off offset:1024
	global_load_dwordx4 v[44:47], v[0:1], off offset:1552
	global_load_dwordx4 v[60:63], v[0:1], off offset:1536
	v_mov_b32_e32 v71, v72
	v_mov_b32_e32 v112, v73
	s_waitcnt vmcnt(0)
	s_branch .LBB0_1075

; __device__ __forceinline__ unsigned xb_add(unsigned* p, unsigned v) { return __hip_atomic_fetch_add(p, v, __ATOMIC_RELAXED, __HIP_MEMORY_SCOPE_AGENT); }
; __device__ __forceinline__ void xcd_barrier(const XcdBarrier& b) {
;     asm volatile("s_waitcnt vmcnt(0)" ::: "memory");
;     __syncthreads();
;     if (threadIdx.x == 0) {
;         unsigned* bar = b.bar;
;         __builtin_amdgcn_s_waitcnt(0);
;         unsigned nloc = b.st[0], nx = b.st[1];
;         if (nloc == 0u) { xcd_barrier_complete(bar, b.x, nloc, nx); b.st[0] = nloc; b.st[1] = nx; }
;         const unsigned old = xb_add(&bar[XB_XSUB(b.x)], 1u);
.LBB0_1088:
	s_setprio 0
	s_or_b64 exec, exec, s[40:41]
	v_readlane_b32 s36, v251, 19
	s_add_i32 s20, s75, 9
	v_readlane_b32 s39, v251, 22
	s_cmp_ge_i32 s20, s39
	v_readlane_b32 s37, v251, 20
	v_readlane_b32 s38, v251, 21
	s_cbranch_scc1 .LBB0_1142
	s_waitcnt vmcnt(0)
	s_waitcnt lgkmcnt(0)
	s_barrier
	s_mov_b64 s[0:1], exec
	v_readlane_b32 s4, v252, 2
	v_readlane_b32 s5, v252, 3
	s_and_b64 s[4:5], s[0:1], s[4:5]
	s_mov_b64 exec, s[4:5]
	s_cbranch_execz .LBB0_1141
	s_waitcnt vmcnt(0) expcnt(0) lgkmcnt(0)
	ds_read_b32 v2, v221
	ds_read_b32 v0, v222
	s_waitcnt lgkmcnt(1)
	v_cmp_ne_u32_e32 vcc, 0, v2
	s_cbranch_vccnz .LBB0_1105
	s_mov_b32 s24, 1
	s_branch .LBB0_1093

; DI int otid() { int t = threadIdx.x; asm volatile("" : "+v"(t)); return t; }
; DI int obid() { int t = blockIdx.x; asm volatile("" : "+s"(t)); return t; }
; DI void expert_vsum(const Params& p, int nrows) {
;   const int tid = otid(), wave = tid >> 6, lane = tid & 63, g = lane >> 3, s = lane & 7;
;   const int bid = obid(), x = bid & 7, jx = bid >> 3, wpx = (gridDim.x + 7 - x) >> 3;
;   const u16* IDX = (const u16*)(p.S + OFF_IDX) + g * 16;
;   const u16* AV = (const u16*)(p.S + OFF_PU) + g * 16;
;   const unsigned char* PV = (const unsigned char*)(p.PT + PT_V) + (size_t)x * 16384 * 128 + s * 16;
;   u16* Y = (u16*)((char*)p.U + (size_t)NROW * 2048 * 2);
;   const int b5 = (lane >> 5) & 1, b4 = (lane >> 4) & 1, b3 = (lane >> 3) & 1;
;   const int tstep = wpx * 4;
;   int t = jx * 4 + wave;
;   uint4 ni[2], na[2];
;   auto prefetch = [&](int tt) {
; #pragma unroll
;     for (int j = 0; j < 2; j++) { ni[j] = *(const uint4*)(IDX + (size_t)tt * 128 + j * 8); na[j] = *(const uint4*)(AV + (size_t)tt * 128 + j * 8); }
;   };
;   if (t < nrows) prefetch(t);
.Lprio_ph_v:
	s_waitcnt vmcnt(1)
	v_mov_b32_e32 v10, v220
	s_mov_b32 s4, s74
	s_ashr_i32 s0, s4, 1
	v_ashrrev_i32_e32 v8, 6, v10
	s_and_b32 s44, s0, -4
	v_add_u32_e32 v88, s44, v8
	v_cmp_gt_i32_e32 vcc, s54, v88
	s_and_saveexec_b64 s[0:1], vcc
	s_cbranch_execz .LBB0_1150
	s_waitcnt lgkmcnt(0)
	v_lshlrev_b32_e32 v0, 2, v10
	v_readlane_b32 s26, v251, 37
	v_readlane_b32 s20, v251, 58
	v_and_b32_e32 v196, 0xe0, v0
	v_readlane_b32 s27, v251, 38
	v_readlane_b32 s21, v251, 59
	v_ashrrev_i32_e32 v89, 31, v88
	v_lshl_add_u64 v[0:1], s[26:27], 0, v[196:197]
	s_waitcnt vmcnt(0)
	v_lshl_add_u64 v[12:13], s[20:21], 0, v[196:197]
	v_lshlrev_b64 v[14:15], 8, v[88:89]
	v_lshl_add_u64 v[4:5], v[0:1], 0, v[14:15]
	v_lshl_add_u64 v[12:13], v[12:13], 0, v[14:15]
	global_load_dwordx4 v[0:3], v[4:5], off offset:16
	s_nop 0
	global_load_dwordx4 v[4:7], v[4:5], off
	s_nop 0
	global_load_dwordx4 v[76:79], v[12:13], off offset:16
	global_load_dwordx4 v[80:83], v[12:13], off
	v_lshlrev_b32_e32 v9, 4, v10
	v_and_b32_e32 v14, 64, v226
	v_and_b32_e32 v12, 0x70, v9
	v_xor_b32_e32 v9, 32, v226
	v_add_u32_e32 v14, 64, v14
	v_cmp_lt_i32_e32 vcc, v9, v14
	s_and_b32 s20, s4, 7
	v_readlane_b32 s4, v252, 36
	v_cndmask_b32_e32 v9, v226, v9, vcc
	v_lshlrev_b32_e32 v89, 2, v9
	v_xor_b32_e32 v9, 16, v226
	v_cmp_lt_i32_e32 vcc, v9, v14
	s_sub_i32 s21, s4, s20
	s_lshl_b32 s4, s20, 21
	v_cndmask_b32_e32 v9, v226, v9, vcc
	v_lshlrev_b32_e32 v97, 2, v9
	v_xor_b32_e32 v9, 8, v226
	v_readlane_b32 s30, v251, 50
	v_cmp_lt_i32_e32 vcc, v9, v14
	v_readlane_b32 s31, v251, 51
	s_add_u32 s4, s30, s4
	v_cndmask_b32_e32 v9, v226, v9, vcc
	s_addc_u32 s5, s31, 0
	v_lshlrev_b32_e32 v99, 2, v9
	v_ashrrev_i32_e32 v9, 31, v8
	s_ashr_i32 s45, s44, 31
	v_mov_b32_e32 v13, v197
	v_lshl_add_u64 v[8:9], v[8:9], 0, s[44:45]
	v_lshl_add_u64 v[90:91], s[4:5], 0, v[12:13]
	v_bfe_u32 v11, v10, 3, 1
	v_bfe_u32 v12, v10, 4, 1
	v_bfe_u32 v13, v10, 5, 1
	v_lshlrev_b64 v[8:9], 11, v[8:9]
	v_and_b32_e32 v10, 7, v10
	v_cmp_eq_u32_e64 s[38:39], 0, v13
	v_lshl_or_b32 v8, s20, 8, v8
	v_lshlrev_b32_e32 v10, 5, v10
	v_lshlrev_b32_e32 v13, 4, v13
	s_lshr_b32 s4, s21, 1
	v_cmp_eq_u32_e64 s[42:43], 0, v11
	v_or3_b32 v8, v8, v10, v13
	v_lshlrev_b32_e32 v10, 3, v12
	v_lshlrev_b32_e32 v11, 2, v11
	v_readlane_b32 s30, v251, 62
	s_and_b32 s4, s4, 0x7ffffffc
	v_or3_b32 v8, v8, v10, v11
	v_readlane_b32 s31, v251, 63
	s_lshr_b32 s24, s21, 3
	v_cmp_eq_u32_e64 s[40:41], 0, v12
	v_lshl_add_u64 v[92:93], s[30:31], 0, v[8:9]
	v_add_u32_e32 v8, s4, v88
	v_ashrrev_i32_e32 v9, 31, v8
	v_lshlrev_b64 v[8:9], 8, v[8:9]
	v_or_b32_e32 v8, v8, v196
	s_lshl_b64 s[46:47], s[24:25], 13
	v_lshl_add_u64 v[94:95], s[26:27], 0, v[8:9]
	s_lshl_b64 s[48:49], s[24:25], 10
	s_mov_b64 s[50:51], 0
	s_branch .LBB0_1148

; __device__ __forceinline__ unsigned xb_add(unsigned* p, unsigned v) { return __hip_atomic_fetch_add(p, v, __ATOMIC_RELAXED, __HIP_MEMORY_SCOPE_AGENT); }
; __device__ __forceinline__ void xcd_barrier(const XcdBarrier& b) {
;     asm volatile("s_waitcnt vmcnt(0)" ::: "memory");
;     __syncthreads();
;     if (threadIdx.x == 0) {
;         unsigned* bar = b.bar;
;         __builtin_amdgcn_s_waitcnt(0);
;         unsigned nloc = b.st[0], nx = b.st[1];
;         if (nloc == 0u) { xcd_barrier_complete(bar, b.x, nloc, nx); b.st[0] = nloc; b.st[1] = nx; }
;         const unsigned old = xb_add(&bar[XB_XSUB(b.x)], 1u);
.LBB0_1150:
	s_setprio 0
	s_or_b64 exec, exec, s[0:1]
	v_readlane_b32 s36, v251, 19
	s_add_i32 s20, s75, 10
	v_readlane_b32 s39, v251, 22
	s_cmp_ge_i32 s20, s39
	v_readlane_b32 s37, v251, 20
	v_readlane_b32 s38, v251, 21
	s_cbranch_scc1 .LBB0_1204
	s_waitcnt vmcnt(0)
	s_waitcnt lgkmcnt(0)
	s_barrier
	s_mov_b64 s[0:1], exec
	v_readlane_b32 s4, v252, 2
	v_readlane_b32 s5, v252, 3
	s_and_b64 s[4:5], s[0:1], s[4:5]
	s_mov_b64 exec, s[4:5]
	s_cbranch_execz .LBB0_1203
	s_waitcnt vmcnt(0) expcnt(0) lgkmcnt(0)
	ds_read_b32 v2, v221
	ds_read_b32 v0, v222
	s_waitcnt lgkmcnt(1)
	v_cmp_ne_u32_e32 vcc, 0, v2
	s_cbranch_vccnz .LBB0_1167
	s_mov_b32 s24, 1
	s_branch .LBB0_1155
